# static priority: s_setprio 1 for waves 4-7 for the whole prompt-attention part of P3 (reset after it)
# baseline (speedup 1.0000x reference)
.LBB0_1884:
	v_readlane_b32 s0, v251, 52
	s_cmp_lt_u32 s0, 4
	s_cbranch_scc1 .Lprio_skip
	s_setprio 1
.Lprio_skip:
	s_nop 0
	s_nop 0
	v_readlane_b32 s3, v251, 5
	s_and_b32 s33, s3, 3
	s_ashr_i32 s0, s3, 6
	s_xor_b32 s39, s33, 7
	s_add_u32 s44, s6, 0x14a00000
	s_addc_u32 s45, s7, 0
	s_ashr_i32 s1, s0, 31
	s_lshl_b64 s[20:21], s[0:1], 11
	s_lshl_b64 s[0:1], s[0:1], 20
	s_cmp_lg_u32 0, -1
	s_waitcnt vmcnt(0)
	v_lshlrev_b32_e32 v2, 1, v0
	s_cselect_b32 s2, 0, 0
	v_and_b32_e32 v2, 32, v2
	s_addk_i32 s2, 0x6000
	v_add_u32_e32 v11, s2, v2
	s_lshl_b32 s2, s3, 5
	s_and_b32 s46, s3, 0xffffffc0
	s_and_b32 s2, s2, 0x780
	s_add_u32 s47, s54, s2
	s_addc_u32 s48, s55, 0
	v_lshlrev_b32_e32 v6, 4, v0
	s_add_u32 s0, s6, s0
	v_lshrrev_b32_e32 v5, 5, v198
	v_and_b32_e32 v6, 0xc0, v6
	s_addc_u32 s1, s7, s1
	s_lshl_b32 s2, s3, 3
	v_lshlrev_b32_e32 v9, 3, v0
	v_lshl_or_b32 v13, v5, 8, v6
	v_lshlrev_b32_e32 v14, 10, v5
	v_lshlrev_b32_e32 v15, 4, v100
	s_and_b32 s2, s2, 0x180
	v_lshlrev_b32_e32 v12, 3, v5
	v_lshlrev_b32_e32 v237, 4, v5
	v_lshlrev_b32_e32 v238, 9, v5
	v_lshrrev_b32_e32 v5, 3, v198
	v_and_b32_e32 v4, 24, v9
	s_add_u32 s0, s0, s2
	v_add3_u32 v235, 0, v14, v15
	v_and_b32_e32 v14, 56, v9
	v_or_b32_e32 v9, 8, v5
	s_addc_u32 s1, s1, 0
	v_lshlrev_b32_e32 v239, 7, v5
	v_lshlrev_b32_e32 v16, 10, v5
	v_lshlrev_b32_e32 v240, 7, v9
	v_lshlrev_b32_e32 v18, 10, v9
	v_or_b32_e32 v9, 16, v5
	v_or_b32_e32 v5, 24, v5
	v_mov_b32_e32 v3, 0
	v_add_u32_e32 v8, 0, v2
	s_add_u32 s24, s0, 0xac00000
	v_lshlrev_b32_e32 v2, 9, v198
	v_lshlrev_b32_e32 v242, 7, v5
	v_lshlrev_b32_e32 v22, 10, v5
	v_lshlrev_b32_e32 v5, 2, v0
	s_addc_u32 s25, s1, 0
	v_lshl_add_u64 v[6:7], s[0:1], 0, v[2:3]
	s_mov_b64 s[0:1], 0xa700000
	v_and_b32_e32 v5, 0x80, v5
	v_lshlrev_b32_e32 v243, 2, v100
	v_lshl_add_u64 v[200:201], v[6:7], 0, s[0:1]
	v_add3_u32 v199, v8, v4, v13
	v_and_b32_e32 v7, 32, v0
	v_or_b32_e32 v2, 0x100, v198
	v_or_b32_e32 v6, 0x140, v198
	v_or_b32_e32 v8, 0x180, v198
	v_or_b32_e32 v10, 0x1c0, v198
	v_lshlrev_b32_e32 v20, 10, v9
	v_add3_u32 v5, v5, v243, 0
	v_lshrrev_b32_e32 v101, 2, v198
	s_mov_b32 s23, 0
	v_or_b32_e32 v228, 0x400, v1
	v_or_b32_e32 v229, 0x800, v1
	v_or_b32_e32 v230, 0xc00, v1
	v_lshlrev_b32_e32 v231, 4, v2
	v_lshlrev_b32_e32 v232, 4, v6
	v_lshlrev_b32_e32 v233, 4, v8
	v_lshlrev_b32_e32 v234, 4, v10
	v_lshlrev_b32_e32 v202, 11, v100
	v_mov_b32_e32 v203, v3
	v_add3_u32 v236, v11, v4, v13
	v_cmp_gt_u32_e64 s[0:1], 32, v198
	v_lshlrev_b32_e32 v241, 7, v9
	v_add_u32_e32 v244, 0x15100, v5
	s_mov_b64 s[2:3], -1
	v_lshlrev_b32_e32 v204, 4, v198
	v_lshlrev_b32_e32 v245, 4, v2
	v_lshlrev_b32_e32 v246, 4, v6
	v_lshlrev_b32_e32 v247, 4, v8
	v_lshlrev_b32_e32 v248, 4, v10
	v_lshlrev_b32_e32 v249, 2, v7
	s_mov_b64 s[26:27], 0x8000
	s_mov_b64 s[28:29], 0x10000
	s_mov_b32 s49, 0xff800000
	s_mov_b32 s50, 0xff61b1e6
	s_mov_b64 s[30:31], 0x18000
	s_mov_b64 s[34:35], 0x20000
	s_mov_b32 s51, 0x41000000
	s_mov_b64 s[36:37], 0x28000
	v_lshlrev_b32_e32 v206, 1, v14
	v_lshlrev_b32_e32 v208, 1, v16
	v_lshlrev_b32_e32 v210, 1, v18
	v_lshlrev_b32_e32 v212, 1, v20
	v_lshlrev_b32_e32 v214, 1, v22
	v_mov_b32_e32 v205, v3
	v_lshlrev_b32_e32 v216, 1, v4
	v_lshlrev_b32_e32 v218, 1, v12
	s_branch .LBB0_1886

.LBB0_1972:
	s_setprio 0
	s_nop 0
	s_cmpk_gt_i32 s38, 0x1ff
	s_cbranch_scc1 .LBB0_2316
	s_lshl_b32 s0, s88, 11
	s_mov_b32 s41, 0
	s_lshl_b32 s40, s88, 5
	v_readlane_b32 s4, v251, 44
	s_add_i32 s34, s0, 0
	s_lshl_b64 s[0:1], s[40:41], 2
	v_readlane_b32 s6, v251, 46
	v_readlane_b32 s7, v251, 47
	s_add_u32 s0, s6, s0
	s_addc_u32 s1, s7, s1
	v_readlane_b32 s5, v251, 45
	s_add_u32 s42, s4, 0x5678000
	s_addc_u32 s43, s5, 0
	v_mov_b32_e32 v101, 0
	s_add_u32 s44, s4, 0x56f8000
	v_readlane_b32 s35, v251, 1
	v_and_b32_e32 v3, 15, v0
	v_readlane_b32 s8, v251, 48
	v_readlane_b32 s9, v251, 49
	v_readlane_b32 s10, v251, 50
	v_readlane_b32 s11, v251, 51
	v_lshl_add_u64 v[6:7], v[100:101], 2, s[0:1]
	s_mov_b64 s[0:1], 0x14c00000
	s_addc_u32 s45, s5, 0
	s_and_b32 s33, s35, 0xffffffc0
	s_lshr_b32 s35, s35, 7
	v_lshlrev_b32_e32 v4, 2, v3
	v_lshl_add_u64 v[74:75], v[6:7], 0, s[0:1]
	v_cmp_eq_u32_e64 s[0:1], 0, v3
	v_cmp_eq_u32_e64 s[2:3], 1, v3
	v_cmp_eq_u32_e64 s[4:5], 2, v3
	v_cmp_eq_u32_e64 s[6:7], 3, v3
	v_cmp_eq_u32_e64 s[8:9], 4, v3
	v_cmp_eq_u32_e64 s[10:11], 5, v3
	v_cmp_eq_u32_e64 s[12:13], 6, v3
	v_cmp_eq_u32_e64 s[14:15], 7, v3
	v_cmp_eq_u32_e64 s[16:17], 8, v3
	v_cmp_eq_u32_e64 s[18:19], 9, v3
	v_cmp_eq_u32_e64 s[20:21], 10, v3
	v_cmp_eq_u32_e64 s[22:23], 11, v3
	v_cmp_eq_u32_e64 s[24:25], 12, v3
	v_cmp_eq_u32_e64 s[26:27], 13, v3
	v_cmp_eq_u32_e64 s[28:29], 14, v3
	v_cmp_eq_u32_e64 s[30:31], 15, v3
	v_and_b32_e32 v5, 48, v198
	v_lshlrev_b32_e32 v3, 6, v3
	s_lshl_b32 s37, s35, 2
	v_add3_u32 v93, s34, v3, v5
	v_and_b32_e32 v3, 48, v0
	s_lshl_b32 s36, s88, 1
	s_add_i32 s37, s37, 0
	v_add_u32_e32 v95, s37, v3
	s_and_b32 s36, s36, 2
	s_lshl_b32 s37, s35, 10
	v_and_b32_e32 v2, 0x300, v1
	v_lshlrev_b32_e32 v6, 2, v198
	s_lshl_b32 s39, s36, 8
	s_add_i32 s37, s37, 0
	v_add_u32_e32 v92, 0, v5
	v_add_u32_e32 v94, s34, v3
	s_lshl_b32 s34, s88, 12
	v_add_u32_e32 v5, 0, v6
	s_add_i32 s37, s37, s39
	v_lshl_add_u32 v76, s35, 6, v2
	v_lshlrev_b32_e32 v78, 1, v4
	v_add_u32_e32 v1, 0, v198
	v_add_u32_e32 v96, s37, v6
	v_ashrrev_i32_e32 v77, 31, v76
	v_mov_b32_e32 v80, v78
	v_mov_b32_e32 v81, v101
	v_lshlrev_b32_e32 v82, 1, v2
	v_mov_b32_e32 v83, v101
	s_movk_i32 s56, 0x800
	s_movk_i32 s57, 0x7f00
	s_movk_i32 s58, 0x7ff
	v_lshlrev_b32_e32 v97, 2, v6
	v_add_u32_e32 v98, s34, v5
	s_lshl_b32 s40, s36, 1
	s_branch .LBB0_1975
